# P1 bias GEMV: the 16 modulation-vector staging loads are issued before the weight loads and stored to LDS from counted waits (no more two-round-trip staging loop)
# speedup vs baseline: 1.0179x; 1.0033x over previous
; #define LAS __attribute__((address_space(3)))
; __device__ __forceinline__ void gemv_load(const float* W, int N, int n0, f32x4 (&wv)[16], int tid) {
;     const int cgp = tid & 7, kg = tid >> 3;
; #pragma unroll
;     for (int i = 0; i < 16; ++i) wv[i] = __builtin_nontemporal_load((const f32x4*)(W + (size_t)(kg + 64 * i) * N + n0 + 4 * cgp));
; }
; __device__ __forceinline__ void phase1(const Params& p, LAS unsigned char* lds, int tid, int lane, int wave) {
;     ...
;     if (blockIdx.x < 176) {
;         LAS float* vecs = (LAS float*)lds; LAS float* red = (LAS float*)(lds + 32768);
;         f32x4 wv[16]; gemv_load(p.w_up, 2 * DFF, 32 * blockIdx.x, wv, tid);
;         for (int i = tid; i < 8192; i += 512) vecs[i] = mod[(i >> 10) * NMOD + 3072 + (i & 1023)];
;         __syncthreads();
.Lgb1_done:
.LBB0_95:
	s_or_b64 exec, exec, s[6:7]
	s_waitcnt lgkmcnt(0)
	s_barrier
	s_load_dwordx2 s[34:35], s[96:97], 0
	s_load_dwordx2 s[4:5], s[96:97], 8
	s_load_dwordx2 s[6:7], s[96:97], 16
	s_load_dwordx2 s[8:9], s[96:97], 24
	s_load_dwordx2 s[38:39], s[96:97], 32
	s_load_dwordx2 s[40:41], s[96:97], 40
	s_load_dwordx2 s[36:37], s[96:97], 48
	s_load_dwordx2 s[10:11], s[96:97], 56
	s_load_dwordx2 s[12:13], s[96:97], 64
	s_load_dwordx2 s[14:15], s[96:97], 72
	s_load_dwordx2 s[42:43], s[96:97], 80
	s_load_dwordx2 s[16:17], s[96:97], 88
	s_load_dwordx2 s[44:45], s[96:97], 96
	s_load_dwordx2 s[18:19], s[96:97], 104
	s_load_dwordx2 s[46:47], s[96:97], 112
	s_load_dwordx2 s[20:21], s[96:97], 120
	s_load_dwordx2 s[30:31], s[96:97], 128
	s_waitcnt lgkmcnt(0)
	s_cmpk_gt_u32 s2, 0xaf
	s_cselect_b64 s[48:49], -1, 0
	s_and_b64 vcc, exec, s[48:49]
	v_lshrrev_b32_e32 v97, 9, v208
	s_cbranch_vccnz .LBB0_112
	s_add_u32 s50, s30, 0x3000
	s_addc_u32 s51, s31, 0
	global_load_dword v136, v96, s[50:51]
	global_load_dword v137, v96, s[50:51] offset:2048
	s_add_u32 s50, s50, 0x6000
	s_addc_u32 s51, s51, 0
	global_load_dword v138, v96, s[50:51]
	global_load_dword v139, v96, s[50:51] offset:2048
	s_add_u32 s50, s50, 0x6000
	s_addc_u32 s51, s51, 0
	global_load_dword v140, v96, s[50:51]
	global_load_dword v141, v96, s[50:51] offset:2048
	s_add_u32 s50, s50, 0x6000
	s_addc_u32 s51, s51, 0
	global_load_dword v142, v96, s[50:51]
	global_load_dword v143, v96, s[50:51] offset:2048
	s_add_u32 s50, s50, 0x6000
	s_addc_u32 s51, s51, 0
	global_load_dword v144, v96, s[50:51]
	global_load_dword v145, v96, s[50:51] offset:2048
	s_add_u32 s50, s50, 0x6000
	s_addc_u32 s51, s51, 0
	global_load_dword v146, v96, s[50:51]
	global_load_dword v147, v96, s[50:51] offset:2048
	s_add_u32 s50, s50, 0x6000
	s_addc_u32 s51, s51, 0
	global_load_dword v148, v96, s[50:51]
	global_load_dword v149, v96, s[50:51] offset:2048
	s_add_u32 s50, s50, 0x6000
	s_addc_u32 s51, s51, 0
	global_load_dword v150, v96, s[50:51]
	global_load_dword v151, v96, s[50:51] offset:2048
	s_lshl_b32 s8, s2, 5
	s_mov_b32 s9, 0
	s_lshl_b64 s[4:5], s[8:9], 2
	s_add_u32 s4, s44, s4
	v_and_b32_e32 v66, 28, v96
	s_addc_u32 s5, s45, s5
	v_mov_b32_e32 v69, 0
	v_lshlrev_b32_e32 v68, 2, v66
	v_mul_u32_u24_e32 v64, 0x1600, v174
	v_lshl_add_u64 v[0:1], s[4:5], 0, v[68:69]
	v_lshlrev_b32_e32 v68, 2, v64
	v_lshl_add_u64 v[56:57], v[0:1], 0, v[68:69]
	s_mov_b32 s0, 0x160000
	v_add_co_u32_e32 v8, vcc, s0, v56
	s_mov_b32 s0, 0x2c0000
	s_nop 0
	v_addc_co_u32_e32 v9, vcc, 0, v57, vcc
	v_add_co_u32_e32 v16, vcc, s0, v56
	s_mov_b32 s0, 0x420000
	s_nop 0
	v_addc_co_u32_e32 v17, vcc, 0, v57, vcc
	v_add_co_u32_e32 v18, vcc, s0, v56
	s_mov_b32 s0, 0x580000
	s_nop 0
	v_addc_co_u32_e32 v19, vcc, 0, v57, vcc
	v_add_co_u32_e32 v24, vcc, s0, v56
	s_mov_b32 s0, 0x6e0000
	s_nop 0
	v_addc_co_u32_e32 v25, vcc, 0, v57, vcc
	v_add_co_u32_e32 v26, vcc, s0, v56
	s_mov_b32 s0, 0x840000
	s_nop 0
	v_addc_co_u32_e32 v27, vcc, 0, v57, vcc
	v_add_co_u32_e32 v32, vcc, s0, v56
	s_mov_b32 s0, 0x9a0000
	s_nop 0
	v_addc_co_u32_e32 v33, vcc, 0, v57, vcc
	v_add_co_u32_e32 v34, vcc, s0, v56
	s_mov_b32 s0, 0xb00000
	s_nop 0
	v_addc_co_u32_e32 v35, vcc, 0, v57, vcc
	v_add_co_u32_e32 v40, vcc, s0, v56
	s_mov_b32 s0, 0xc60000
	s_nop 0
	v_addc_co_u32_e32 v41, vcc, 0, v57, vcc
	v_add_co_u32_e32 v42, vcc, s0, v56
	s_mov_b32 s0, 0xdc0000
	s_nop 0
	v_addc_co_u32_e32 v43, vcc, 0, v57, vcc
	v_add_co_u32_e32 v48, vcc, s0, v56
	s_mov_b32 s0, 0xf20000
	s_nop 0
	v_addc_co_u32_e32 v49, vcc, 0, v57, vcc
	v_add_co_u32_e32 v50, vcc, s0, v56
	s_mov_b32 s0, 0x1080000
	s_nop 0
	v_addc_co_u32_e32 v51, vcc, 0, v57, vcc
	v_add_co_u32_e32 v58, vcc, s0, v56
	s_mov_b32 s0, 0x11e0000
	s_nop 0
	v_addc_co_u32_e32 v59, vcc, 0, v57, vcc
	v_add_co_u32_e32 v60, vcc, s0, v56
	s_mov_b32 s0, 0x1340000
	s_nop 0
	v_addc_co_u32_e32 v61, vcc, 0, v57, vcc
	v_add_co_u32_e32 v70, vcc, s0, v56
	s_mov_b32 s0, 0x14a0000
	s_nop 0
	v_addc_co_u32_e32 v71, vcc, 0, v57, vcc
	v_add_co_u32_e32 v72, vcc, s0, v56
	global_load_dwordx4 v[0:3], v[56:57], off nt
	global_load_dwordx4 v[4:7], v[8:9], off nt
	s_nop 0
	global_load_dwordx4 v[8:11], v[16:17], off nt
	global_load_dwordx4 v[12:15], v[18:19], off nt
	s_nop 0
	global_load_dwordx4 v[16:19], v[24:25], off nt
	global_load_dwordx4 v[20:23], v[26:27], off nt
	s_nop 0
	global_load_dwordx4 v[24:27], v[32:33], off nt
	global_load_dwordx4 v[28:31], v[34:35], off nt
	s_nop 0
	global_load_dwordx4 v[32:35], v[40:41], off nt
	global_load_dwordx4 v[36:39], v[42:43], off nt
	s_nop 0
	global_load_dwordx4 v[40:43], v[48:49], off nt
	global_load_dwordx4 v[44:47], v[50:51], off nt
	s_nop 0
	global_load_dwordx4 v[48:51], v[58:59], off nt
	global_load_dwordx4 v[52:55], v[60:61], off nt
	v_addc_co_u32_e32 v73, vcc, 0, v57, vcc
	global_load_dwordx4 v[56:59], v[70:71], off nt
	global_load_dwordx4 v[60:63], v[72:73], off nt
	s_waitcnt vmcnt(31)
	ds_write_b32 v96, v136
	s_waitcnt vmcnt(30)
	ds_write_b32 v96, v137 offset:2048
	s_waitcnt vmcnt(29)
	ds_write_b32 v96, v138 offset:4096
	s_waitcnt vmcnt(28)
	ds_write_b32 v96, v139 offset:6144
	s_waitcnt vmcnt(27)
	ds_write_b32 v96, v140 offset:8192
	s_waitcnt vmcnt(26)
	ds_write_b32 v96, v141 offset:10240
	s_waitcnt vmcnt(25)
	ds_write_b32 v96, v142 offset:12288
	s_waitcnt vmcnt(24)
	ds_write_b32 v96, v143 offset:14336
	s_waitcnt vmcnt(23)
	ds_write_b32 v96, v144 offset:16384
	s_waitcnt vmcnt(22)
	ds_write_b32 v96, v145 offset:18432
	s_waitcnt vmcnt(21)
	ds_write_b32 v96, v146 offset:20480
	s_waitcnt vmcnt(20)
	ds_write_b32 v96, v147 offset:22528
	s_waitcnt vmcnt(19)
	ds_write_b32 v96, v148 offset:24576
	s_waitcnt vmcnt(18)
	ds_write_b32 v96, v149 offset:26624
	s_waitcnt vmcnt(17)
	ds_write_b32 v96, v150 offset:28672
	s_waitcnt vmcnt(16)
	ds_write_b32 v96, v151 offset:30720
	s_waitcnt vmcnt(0)
.LBB0_104:
	v_lshrrev_b32_e32 v67, 5, v208
	v_lshlrev_b32_e32 v66, 2, v66
	v_lshlrev_b32_e32 v65, 7, v208
	v_mul_u32_u24_e32 v70, 0x1600, v67
	v_mov_b32_e32 v67, 0
	v_add_u32_e32 v76, 0, v66
	v_and_b32_e32 v77, 0x1fc00, v65
	v_or_b32_e32 v78, 0x380, v65
	v_and_b32_e32 v65, 31, v208
	v_lshl_add_u64 v[68:69], s[44:45], 0, v[66:67]
	v_lshlrev_b32_e32 v66, 2, v70
	s_movk_i32 s0, 0x380
	v_lshl_add_u64 v[70:71], s[30:31], 0, v[66:67]
	v_lshlrev_b32_e32 v66, 2, v65
	v_lshlrev_b32_e32 v64, 2, v64
	v_mov_b32_e32 v65, v67
	v_lshl_add_u64 v[74:75], v[68:69], 0, v[64:65]
	v_and_or_b32 v64, v96, s0, v66
	s_movk_i32 s1, 0x100
	v_lshl_add_u64 v[70:71], v[70:71], 0, v[66:67]
	s_mov_b64 s[4:5], 0x40000
	v_add_u32_e32 v64, 0, v64
	v_lshl_add_u32 v120, v174, 2, 0
	v_cmp_gt_u32_e64 s[6:7], s1, v208
	v_lshl_add_u64 v[72:73], v[70:71], 0, s[4:5]
	v_add_u32_e32 v121, 0x8000, v64
	v_add_u32_e32 v122, v76, v77
	v_add_u32_e32 v123, v76, v78
	s_mov_b32 s4, s2
	s_waitcnt lgkmcnt(0)
	s_barrier
	s_branch .LBB0_106
